# seams G2->G3, G3->G4, G4->G5, G6->G7, G7->G8: barrier among the 4 workgroups that share a token tile (same XCD) instead of the whole XCD
# speedup vs baseline: 1.0119x; 1.0054x over previous
.LBB0_689:
	s_waitcnt vmcnt(0)
	v_readfirstlane_b32 s3, v194
	s_cmp_gt_u32 s3, 63
	s_waitcnt lgkmcnt(0)
	s_barrier
	s_cbranch_scc1 .LBB0_743
	v_mbcnt_lo_u32_b32 v0, -1, 0
	v_mbcnt_hi_u32_b32 v0, -1, v0
	s_nop 0
	v_cmp_eq_u32_e32 vcc, 0, v0
	s_and_saveexec_b64 s[6:7], vcc
	s_cbranch_execz .LBB0_742
	v_mov_b32_e32 v20, 0x23ff0
	s_waitcnt vmcnt(0) lgkmcnt(0)
	ds_read_b128 v[20:23], v20
	s_waitcnt lgkmcnt(0)
	v_readfirstlane_b32 s3, v22
	s_nop 0
	s_cmp_eq_u32 s3, 0
	s_cbranch_scc1 .Lfb_slow_2
	v_readfirstlane_b32 s8, v20
	s_cmp_eq_u32 s8, 32
	s_cbranch_scc0 .Lfb_xcd_2
	buffer_inv sc1
	s_getreg_b32 s3, hwreg(HW_REG_XCC_ID, 0, 4)
	s_and_b32 s3, s3, 7
	s_lshl_b32 s3, s3, 8
	s_bfe_u32 s8, s2, 0x30003
	s_lshl_b32 s8, s8, 2
	s_add_u32 s3, s3, s8
	s_add_u32 s3, s3, 0x36c0
	s_add_u32 s4, s92, 0x510000
	s_addc_u32 s5, s93, 0
	v_mov_b32_e32 v26, s3
	v_mov_b32_e32 v27, 1
	v_mov_b32_e32 v25, 4
	global_atomic_add v26, v27, s[4:5]
	s_mov_b32 s8, 0
	s_branch .Lfb_spin_2
.Lfb_xcd_2:
	buffer_inv sc1
	v_add_u32_e32 v23, 1, v23
	v_mov_b32_e32 v24, 0x23ffc
	ds_write_b32 v24, v23
	v_mul_lo_u32 v25, v23, v20
	s_getreg_b32 s3, hwreg(HW_REG_XCC_ID, 0, 4)
	s_and_b32 s3, s3, 7
	s_lshl_b32 s3, s3, 8
	s_add_u32 s3, s3, 0x3680
	s_add_u32 s4, s92, 0x510000
	s_addc_u32 s5, s93, 0
	v_mov_b32_e32 v26, s3
	v_mov_b32_e32 v27, 1
	global_atomic_add v26, v27, s[4:5]
	s_mov_b32 s8, 0

.LBB0_772:
	s_waitcnt vmcnt(0)
	v_readfirstlane_b32 s0, v194
	s_cmp_gt_u32 s0, 63
	s_waitcnt vmcnt(0)
	s_barrier
	s_cbranch_scc1 .LBB0_826
	v_mbcnt_lo_u32_b32 v0, -1, 0
	v_mbcnt_hi_u32_b32 v0, -1, v0
	s_nop 0
	v_cmp_eq_u32_e32 vcc, 0, v0
	s_and_saveexec_b64 s[0:1], vcc
	s_cbranch_execz .LBB0_825
	v_mov_b32_e32 v20, 0x23ff0
	s_waitcnt vmcnt(0) lgkmcnt(0)
	ds_read_b128 v[20:23], v20
	s_waitcnt lgkmcnt(0)
	v_readfirstlane_b32 s3, v22
	s_nop 0
	s_cmp_eq_u32 s3, 0
	s_cbranch_scc1 .Lfb_slow_3
	v_readfirstlane_b32 s8, v20
	s_cmp_eq_u32 s8, 32
	s_cbranch_scc0 .Lfb_xcd_3
	buffer_inv sc1
	s_getreg_b32 s3, hwreg(HW_REG_XCC_ID, 0, 4)
	s_and_b32 s3, s3, 7
	s_lshl_b32 s3, s3, 8
	s_bfe_u32 s8, s2, 0x30003
	s_lshl_b32 s8, s8, 2
	s_add_u32 s3, s3, s8
	s_add_u32 s3, s3, 0x36c0
	s_add_u32 s4, s92, 0x510000
	s_addc_u32 s5, s93, 0
	v_mov_b32_e32 v26, s3
	v_mov_b32_e32 v27, 1
	v_mov_b32_e32 v25, 8
	global_atomic_add v26, v27, s[4:5]
	s_mov_b32 s8, 0
	s_branch .Lfb_spin_3

.LBB0_864:
	s_waitcnt vmcnt(0)
	v_readfirstlane_b32 s3, v194
	s_cmp_gt_u32 s3, 63
	s_waitcnt lgkmcnt(0)
	s_barrier
	s_cbranch_scc1 .LBB0_918
	v_mbcnt_lo_u32_b32 v0, -1, 0
	v_mbcnt_hi_u32_b32 v0, -1, v0
	s_nop 0
	v_cmp_eq_u32_e32 vcc, 0, v0
	s_and_saveexec_b64 s[6:7], vcc
	s_cbranch_execz .LBB0_917
	v_mov_b32_e32 v20, 0x23ff0
	s_waitcnt vmcnt(0) lgkmcnt(0)
	ds_read_b128 v[20:23], v20
	s_waitcnt lgkmcnt(0)
	v_readfirstlane_b32 s3, v22
	s_nop 0
	s_cmp_eq_u32 s3, 0
	s_cbranch_scc1 .Lfb_slow_4
	v_readfirstlane_b32 s8, v20
	s_cmp_eq_u32 s8, 32
	s_cbranch_scc0 .Lfb_xcd_4
	buffer_inv sc1
	s_getreg_b32 s3, hwreg(HW_REG_XCC_ID, 0, 4)
	s_and_b32 s3, s3, 7
	s_lshl_b32 s3, s3, 8
	s_bfe_u32 s8, s2, 0x30003
	s_lshl_b32 s8, s8, 2
	s_add_u32 s3, s3, s8
	s_add_u32 s3, s3, 0x36c0
	s_add_u32 s4, s92, 0x510000
	s_addc_u32 s5, s93, 0
	v_mov_b32_e32 v26, s3
	v_mov_b32_e32 v27, 1
	v_mov_b32_e32 v25, 12
	global_atomic_add v26, v27, s[4:5]
	s_mov_b32 s8, 0
	s_branch .Lfb_spin_4

.LBB0_1249:
	s_waitcnt vmcnt(0)
	v_readfirstlane_b32 s3, v194
	s_cmp_gt_u32 s3, 63
	s_waitcnt lgkmcnt(0)
	s_barrier
	s_cbranch_scc1 .LBB0_1303
	v_mbcnt_lo_u32_b32 v0, -1, 0
	v_mbcnt_hi_u32_b32 v0, -1, v0
	s_nop 0
	v_cmp_eq_u32_e32 vcc, 0, v0
	s_and_saveexec_b64 s[6:7], vcc
	s_cbranch_execz .LBB0_1302
	v_mov_b32_e32 v20, 0x23ff0
	s_waitcnt vmcnt(0) lgkmcnt(0)
	ds_read_b128 v[20:23], v20
	s_waitcnt lgkmcnt(0)
	v_readfirstlane_b32 s3, v22
	s_nop 0
	s_cmp_eq_u32 s3, 0
	s_cbranch_scc1 .Lfb_slow_7
	v_readfirstlane_b32 s8, v20
	s_cmp_eq_u32 s8, 32
	s_cbranch_scc0 .Lfb_xcd_7
	buffer_inv sc1
	s_getreg_b32 s3, hwreg(HW_REG_XCC_ID, 0, 4)
	s_and_b32 s3, s3, 7
	s_lshl_b32 s3, s3, 8
	s_bfe_u32 s8, s2, 0x30003
	s_lshl_b32 s8, s8, 2
	s_add_u32 s3, s3, s8
	s_add_u32 s3, s3, 0x36c0
	s_add_u32 s4, s92, 0x510000
	s_addc_u32 s5, s93, 0
	v_mov_b32_e32 v26, s3
	v_mov_b32_e32 v27, 1
	v_mov_b32_e32 v25, 16
	global_atomic_add v26, v27, s[4:5]
	s_mov_b32 s8, 0
	s_branch .Lfb_spin_7

.LBB0_1332:
	s_waitcnt vmcnt(0)
	v_readfirstlane_b32 s0, v194
	s_cmp_gt_u32 s0, 63
	s_waitcnt vmcnt(0)
	s_barrier
	s_cbranch_scc1 .LBB0_1386
	v_mbcnt_lo_u32_b32 v0, -1, 0
	v_mbcnt_hi_u32_b32 v0, -1, v0
	s_nop 0
	v_cmp_eq_u32_e32 vcc, 0, v0
	s_and_saveexec_b64 s[0:1], vcc
	s_cbranch_execz .LBB0_1385
	v_mov_b32_e32 v20, 0x23ff0
	s_waitcnt vmcnt(0) lgkmcnt(0)
	ds_read_b128 v[20:23], v20
	s_waitcnt lgkmcnt(0)
	v_readfirstlane_b32 s3, v22
	s_nop 0
	s_cmp_eq_u32 s3, 0
	s_cbranch_scc1 .Lfb_slow_8
	v_readfirstlane_b32 s8, v20
	s_cmp_eq_u32 s8, 32
	s_cbranch_scc0 .Lfb_xcd_8
	buffer_inv sc1
	s_getreg_b32 s3, hwreg(HW_REG_XCC_ID, 0, 4)
	s_and_b32 s3, s3, 7
	s_lshl_b32 s3, s3, 8
	s_bfe_u32 s8, s2, 0x30003
	s_lshl_b32 s8, s8, 2
	s_add_u32 s3, s3, s8
	s_add_u32 s3, s3, 0x36c0
	s_add_u32 s4, s92, 0x510000
	s_addc_u32 s5, s93, 0
	v_mov_b32_e32 v26, s3
	v_mov_b32_e32 v27, 1
	v_mov_b32_e32 v25, 20
	global_atomic_add v26, v27, s[4:5]
	s_mov_b32 s8, 0
	s_branch .Lfb_spin_8
